# NP3: no s_setprio toggling in the memory K/V tile GEMM loop either (all priority toggles removed), on top of v082
# baseline (speedup 1.0000x reference)
.LBB0_264:
	s_add_i32 s0, s46, 1
	s_cmp_lg_u32 s0, 4
	s_cselect_b32 s46, s0, 0
	s_lshl_b32 s0, s46, 15
	v_add_u32_e32 v130, s0, v193
	v_add_u32_e32 v138, s0, v194
	ds_read_b128 v[134:137], v130
	ds_read_b128 v[130:133], v130 offset:2048
	ds_read_b128 v[150:153], v138 offset:16384
	ds_read_b128 v[146:149], v138 offset:18432
	ds_read_b128 v[142:145], v138 offset:20480
	ds_read_b128 v[138:141], v138 offset:22528
	v_mfma_f32_32x32x16_bf16 v[114:129], v[174:177], v[158:161], v[114:129]
	v_mfma_f32_32x32x16_bf16 v[50:65], v[174:177], v[154:157], v[50:65]
	v_mfma_f32_32x32x16_bf16 v[98:113], v[170:173], v[158:161], v[98:113]
	v_mfma_f32_32x32x16_bf16 v[34:49], v[170:173], v[154:157], v[34:49]
	v_mfma_f32_32x32x16_bf16 v[82:97], v[166:169], v[158:161], v[82:97]
	v_mfma_f32_32x32x16_bf16 v[18:33], v[166:169], v[154:157], v[18:33]
	v_mfma_f32_32x32x16_bf16 v[66:81], v[162:165], v[158:161], v[66:81]
	v_mfma_f32_32x32x16_bf16 v[2:17], v[162:165], v[154:157], v[2:17]
	s_waitcnt lgkmcnt(0)
	s_add_u32 s40, s40, 64
	s_addc_u32 s41, s41, 0
	s_add_i32 s34, s34, 1
	s_cmpk_eq_i32 s40, 0x780
	s_cbranch_scc1 .LBB0_267
.LBB0_265:
	s_lshl_b32 s0, s46, 15
	s_add_i32 s0, s0, 0
	v_add3_u32 v154, s0, v189, v192
	v_add3_u32 v162, s0, v190, v192
	ds_read_b128 v[158:161], v154
	ds_read_b128 v[154:157], v154 offset:2048
	ds_read_b128 v[174:177], v162 offset:16384
	ds_read_b128 v[170:173], v162 offset:18432
	ds_read_b128 v[166:169], v162 offset:20480
	ds_read_b128 v[162:165], v162 offset:22528
	v_mfma_f32_32x32x16_bf16 v[114:129], v[150:153], v[134:137], v[114:129]
	v_mfma_f32_32x32x16_bf16 v[50:65], v[150:153], v[130:133], v[50:65]
	v_mfma_f32_32x32x16_bf16 v[98:113], v[146:149], v[134:137], v[98:113]
	v_mfma_f32_32x32x16_bf16 v[34:49], v[146:149], v[130:133], v[34:49]
	v_mfma_f32_32x32x16_bf16 v[82:97], v[142:145], v[134:137], v[82:97]
	v_mfma_f32_32x32x16_bf16 v[18:33], v[142:145], v[130:133], v[18:33]
	v_mfma_f32_32x32x16_bf16 v[66:81], v[138:141], v[134:137], v[66:81]
	v_mfma_f32_32x32x16_bf16 v[2:17], v[138:141], v[130:133], v[2:17]
	s_waitcnt lgkmcnt(0)
	s_waitcnt vmcnt(4)
	s_cmp_gt_u32 s34, 28
	s_barrier
	s_cbranch_scc1 .LBB0_264
	s_cmp_gt_i32 s46, 0
	s_cselect_b32 s0, -1, 3
	s_add_i32 s0, s0, s46
	v_lshl_add_u32 v134, s0, 15, v191
	v_lshl_add_u64 v[130:131], v[180:181], 0, s[40:41]
	s_mov_b64 s[42:43], 0xc0
	v_readfirstlane_b32 s0, v134
	v_lshl_add_u64 v[132:133], v[130:131], 0, s[42:43]
	s_mov_b32 m0, s0
	v_lshl_add_u64 v[130:131], v[130:131], 0, s[26:27]
	global_load_lds_dwordx4 v[132:133], off
	v_add_u32_e32 v132, 0x2000, v134
	v_add_u32_e32 v135, 0x4000, v134
	v_readfirstlane_b32 s0, v132
	s_mov_b32 m0, s0
	v_readfirstlane_b32 s0, v135
	global_load_lds_dwordx4 v[130:131], off
	v_lshl_add_u64 v[130:131], v[178:179], 0, s[40:41]
	v_lshl_add_u64 v[132:133], v[130:131], 0, s[42:43]
	s_mov_b32 m0, s0
	v_lshl_add_u64 v[130:131], v[130:131], 0, s[26:27]
	global_load_lds_dwordx4 v[132:133], off
	v_add_u32_e32 v132, 0x6000, v134
	s_nop 0
	v_readfirstlane_b32 s0, v132
	s_mov_b32 m0, s0
	s_nop 0
	global_load_lds_dwordx4 v[130:131], off
	s_branch .LBB0_264
.LBB0_267:
	s_add_i32 s0, s0, 0
	v_add3_u32 v158, s0, v189, v192
	v_add3_u32 v174, s0, v190, v192
	ds_read_b128 v[154:157], v158
	ds_read_b128 v[158:161], v158 offset:2048
	ds_read_b128 v[162:165], v174 offset:16384
	ds_read_b128 v[166:169], v174 offset:18432
	ds_read_b128 v[170:173], v174 offset:20480
	ds_read_b128 v[174:177], v174 offset:22528
	v_mfma_f32_32x32x16_bf16 v[114:129], v[150:153], v[134:137], v[114:129]
	v_mfma_f32_32x32x16_bf16 v[50:65], v[150:153], v[130:133], v[50:65]
	v_mfma_f32_32x32x16_bf16 v[98:113], v[146:149], v[134:137], v[98:113]
	v_mfma_f32_32x32x16_bf16 v[34:49], v[146:149], v[130:133], v[34:49]
	v_mfma_f32_32x32x16_bf16 v[82:97], v[142:145], v[134:137], v[82:97]
	v_mfma_f32_32x32x16_bf16 v[18:33], v[142:145], v[130:133], v[18:33]
	v_mfma_f32_32x32x16_bf16 v[66:81], v[138:141], v[134:137], v[66:81]
	v_mfma_f32_32x32x16_bf16 v[2:17], v[138:141], v[130:133], v[2:17]
	s_waitcnt lgkmcnt(0)
	s_add_i32 s0, s46, 1
	s_lshl_b32 s1, s0, 15
	s_cmp_lg_u32 s0, 4
	s_cselect_b32 s0, s1, 0
	v_add_u32_e32 v134, s0, v193
	v_add_u32_e32 v150, s0, v194
	s_waitcnt vmcnt(0)
	s_barrier
	ds_read_b128 v[130:133], v134
	ds_read_b128 v[134:137], v134 offset:2048
	ds_read_b128 v[138:141], v150 offset:16384
	ds_read_b128 v[142:145], v150 offset:18432
	ds_read_b128 v[146:149], v150 offset:20480
	ds_read_b128 v[150:153], v150 offset:22528
	v_mfma_f32_32x32x16_bf16 v[114:129], v[162:165], v[154:157], v[114:129]
	v_mfma_f32_32x32x16_bf16 v[50:65], v[162:165], v[158:161], v[50:65]
	v_mfma_f32_32x32x16_bf16 v[98:113], v[166:169], v[154:157], v[98:113]
	v_mfma_f32_32x32x16_bf16 v[34:49], v[166:169], v[158:161], v[34:49]
	v_mfma_f32_32x32x16_bf16 v[82:97], v[170:173], v[154:157], v[82:97]
	v_mfma_f32_32x32x16_bf16 v[18:33], v[170:173], v[158:161], v[18:33]
	v_mfma_f32_32x32x16_bf16 v[66:81], v[174:177], v[154:157], v[66:81]
	v_mfma_f32_32x32x16_bf16 v[2:17], v[174:177], v[158:161], v[2:17]
	s_waitcnt lgkmcnt(0)
	s_add_i32 s0, s0, 0
	v_add3_u32 v158, s0, v189, v192
	v_add3_u32 v174, s0, v190, v192
	ds_read_b128 v[154:157], v158
	ds_read_b128 v[158:161], v158 offset:2048
	ds_read_b128 v[162:165], v174 offset:16384
	ds_read_b128 v[166:169], v174 offset:18432
	ds_read_b128 v[170:173], v174 offset:20480
	ds_read_b128 v[174:177], v174 offset:22528
	v_mfma_f32_32x32x16_bf16 v[114:129], v[138:141], v[130:133], v[114:129]
	v_mfma_f32_32x32x16_bf16 v[50:65], v[138:141], v[134:137], v[50:65]
	v_mfma_f32_32x32x16_bf16 v[98:113], v[142:145], v[130:133], v[98:113]
	v_mfma_f32_32x32x16_bf16 v[34:49], v[142:145], v[134:137], v[34:49]
	v_mfma_f32_32x32x16_bf16 v[82:97], v[146:149], v[130:133], v[82:97]
	v_mfma_f32_32x32x16_bf16 v[18:33], v[146:149], v[134:137], v[18:33]
	v_mfma_f32_32x32x16_bf16 v[66:81], v[150:153], v[130:133], v[66:81]
	v_mfma_f32_32x32x16_bf16 v[2:17], v[150:153], v[134:137], v[2:17]
	s_waitcnt lgkmcnt(0)
	v_mfma_f32_32x32x16_bf16 v[114:129], v[162:165], v[154:157], v[114:129]
	v_mfma_f32_32x32x16_bf16 v[50:65], v[162:165], v[158:161], v[50:65]
	v_mfma_f32_32x32x16_bf16 v[98:113], v[166:169], v[154:157], v[98:113]
	v_mfma_f32_32x32x16_bf16 v[34:49], v[166:169], v[158:161], v[34:49]
	v_mfma_f32_32x32x16_bf16 v[82:97], v[170:173], v[154:157], v[82:97]
	v_mfma_f32_32x32x16_bf16 v[18:33], v[170:173], v[158:161], v[18:33]
	v_mfma_f32_32x32x16_bf16 v[66:81], v[174:177], v[154:157], v[66:81]
	v_mfma_f32_32x32x16_bf16 v[2:17], v[174:177], v[158:161], v[2:17]
	s_waitcnt lgkmcnt(0)
	v_and_b32_e32 v131, 0xc0, v182
	v_or_b32_e32 v135, s45, v131
	s_cmp_lg_u64 s[38:39], 0
	s_cselect_b64 s[34:35], -1, 0
	v_or_b32_e32 v132, v135, v185
	v_mov_b32_e32 v130, 1.0
	s_and_b64 vcc, exec, s[34:35]
	v_ashrrev_i32_e32 v133, 31, v132
	v_mov_b32_e32 v134, 1.0
	s_waitcnt vmcnt(0)
	s_barrier
	s_cbranch_vccz .LBB0_269
	v_lshl_add_u64 v[136:137], v[132:133], 2, s[38:39]
	global_load_dword v134, v[136:137], off
	s_waitcnt vmcnt(0)
	v_fmamk_f32 v134, v134, 0x3a800000, v221
	v_rsq_f32_e32 v134, v134
